# N2 step loop: fast-path entry and common tail (both taken-branch targets every step) placed on 64-byte boundaries
# speedup vs baseline: 1.0025x; 1.0025x over previous
; __device__ __forceinline__ float exp2f_(float x) { return __builtin_amdgcn_exp2f(x); }
; __device__ __forceinline__ f32x4 mfma16(bf16x8 a, bf16x8 b, f32x4 c) { return __builtin_amdgcn_mfma_f32_16x16x32_bf16(a, b, c, 0, 0, 0); }
; __device__ __forceinline__ void nsa_block_step(const bf16_t* Ks, const bf16_t* VT, const bf16x8 (&qf)[2][2], f32x4 (&O)[2][4], float (&m)[2], float (&l)[2],
;                                                int klo, int khi, int r, int q) {
;     ...
;     bf16x8 pbv[2][2];
; #pragma unroll
;     for (int x = 0; x < 2; x++) {
;         float mx = fmaxf(fmaxf(fmaxf(s[x][0][0], s[x][0][1]), fmaxf(s[x][0][2], s[x][0][3])), fmaxf(fmaxf(s[x][1][0], s[x][1][1]), fmaxf(s[x][1][2], s[x][1][3])));
;         mx = fmaxf(mx, fmaxf(fmaxf(fmaxf(s[x][2][0], s[x][2][1]), fmaxf(s[x][2][2], s[x][2][3])), fmaxf(fmaxf(s[x][3][0], s[x][3][1]), fmaxf(s[x][3][2], s[x][3][3]))));
;         mx = xrow_max(mx);
;         const float mnew = fmaxf(m[x], mx);
;         const float alpha = exp2f_(m[x] - mnew);
;         m[x] = mnew;
;         float ls = 0.f;
; #pragma unroll
;         for (int kt = 0; kt < 4; kt++)
; #pragma unroll
;             for (int j = 0; j < 4; j++) { const float pv = exp2f_(s[x][kt][j] - mnew); s[x][kt][j] = pv; ls += pv; }
;         l[x] = l[x] * alpha + ls;
; #pragma unroll
;         for (int dt = 0; dt < 4; dt++) O[x][dt] *= alpha;
; #pragma unroll
;         for (int s2 = 0; s2 < 2; s2++) {
;             const u32x4 t4 = {pack2(s[x][2 * s2][0], s[x][2 * s2][1]), pack2(s[x][2 * s2][2], s[x][2 * s2][3]),
;                               pack2(s[x][2 * s2 + 1][0], s[x][2 * s2 + 1][1]), pack2(s[x][2 * s2 + 1][2], s[x][2 * s2 + 1][3])};
;             pbv[x][s2] = __builtin_bit_cast(bf16x8, t4);
;         }
;     }
; #pragma unroll
;     for (int s2 = 0; s2 < 2; s2++)
; #pragma unroll
;         for (int dt = 0; dt < 4; dt++) {
;             const u32x2 lo = *(const u32x2*)(VT + (dt * 16 + r) * 72 + (2 * s2) * 16 + 4 * q);
;             const u32x2 hi = *(const u32x2*)(VT + (dt * 16 + r) * 72 + (2 * s2 + 1) * 16 + 4 * q);
;             const bf16x8 va = mk_frag(lo, hi);
; #pragma unroll
;             for (int x = 0; x < 2; x++) O[x][dt] = mfma16(va, pbv[x][s2], O[x][dt]);
;         }
.LBB0_628:
	v_max3_f32 v88, v80, v81, v82
	v_max3_f32 v164, v68, v69, v70
	v_max3_f32 v97, v72, v73, v74
	v_max3_f32 v165, v64, v65, v66
	v_max3_f32 v104, v84, v85, v86
	v_max3_f32 v166, v60, v61, v62
	v_max3_f32 v105, v76, v77, v78
	v_max3_f32 v167, v56, v57, v58
	v_max3_f32 v88, v88, v83, v75
	v_max3_f32 v164, v164, v71, v67
	v_max3_f32 v97, v97, v87, v79
	v_max3_f32 v165, v165, v63, v59
	v_max3_f32 v88, v88, v97, v104
	v_max3_f32 v164, v164, v165, v166
	v_max_f32_e32 v88, v88, v105
	v_max_f32_e32 v164, v164, v167
	v_cmp_gt_f32_e32 vcc, v88, v178
	v_cmp_gt_f32_e64 s[46:47], v164, v179
	s_or_b64 vcc, vcc, s[46:47]
	s_cbranch_vccz .Ln2_fast
	v_add_f32_e32 v180, v103, v176
	v_add_f32_e32 v182, v102, v177
	v_mov_b32_e32 v97, v88
	v_mov_b32_e32 v165, v164
	s_nop 0
	v_permlane16_swap_b32_e32 v88, v97
	s_nop 0
	v_permlane16_swap_b32_e32 v164, v165
	v_max_f32_e32 v88, v88, v97
	v_max_f32_e32 v164, v164, v165
	v_mov_b32_e32 v97, v88
	v_mov_b32_e32 v165, v164
	s_nop 0
	v_permlane32_swap_b32_e32 v88, v97
	s_nop 0
	v_permlane32_swap_b32_e32 v164, v165
	v_max3_f32 v88, v180, v88, v97
	v_sub_f32_e32 v72, v72, v88
	v_exp_f32_e32 v105, v72
	v_sub_f32_e32 v72, v73, v88
	v_exp_f32_e32 v109, v72
	v_sub_f32_e32 v72, v74, v88
	v_exp_f32_e32 v107, v72
	v_sub_f32_e32 v72, v75, v88
	v_sub_f32_e32 v80, v80, v88
	v_exp_f32_e32 v111, v72
	v_sub_f32_e32 v72, v84, v88
	v_exp_f32_e32 v117, v80
	v_sub_f32_e32 v80, v81, v88
	v_exp_f32_e32 v73, v72
	v_sub_f32_e32 v72, v85, v88
	v_exp_f32_e32 v113, v80
	v_sub_f32_e32 v80, v82, v88
	v_exp_f32_e32 v75, v72
	v_sub_f32_e32 v72, v86, v88
	v_exp_f32_e32 v115, v80
	v_sub_f32_e32 v80, v83, v88
	v_exp_f32_e32 v83, v72
	v_sub_f32_e32 v72, v87, v88
	v_exp_f32_e32 v81, v72
	v_sub_f32_e32 v72, v76, v88
	v_exp_f32_e32 v85, v72
	v_sub_f32_e32 v72, v77, v88
	v_exp_f32_e32 v87, v72
	v_sub_f32_e32 v72, v78, v88
	v_exp_f32_e32 v77, v72
	v_sub_f32_e32 v72, v79, v88
	v_exp_f32_e32 v79, v72
	v_sub_f32_e32 v97, v180, v88
	v_exp_f32_e32 v103, v80
	v_exp_f32_e32 v76, v97
	v_max3_f32 v97, v182, v164, v165
	v_sub_f32_e32 v64, v64, v97
	v_sub_f32_e32 v68, v68, v97
	v_exp_f32_e32 v104, v64
	v_sub_f32_e32 v64, v65, v97
	v_sub_f32_e32 v78, v182, v97
	v_exp_f32_e32 v116, v68
	v_sub_f32_e32 v68, v69, v97
	v_exp_f32_e32 v108, v64
	v_sub_f32_e32 v64, v66, v97
	v_exp_f32_e32 v112, v68
	v_exp_f32_e32 v106, v64
	v_sub_f32_e32 v64, v67, v97
	v_sub_f32_e32 v60, v60, v97
	v_exp_f32_e32 v160, v78
	v_add_u32_e32 v78, 0x4800, v135
	v_exp_f32_e32 v110, v64
	v_exp_f32_e32 v72, v60
	v_sub_f32_e32 v60, v61, v97
	ds_read2_b64 v[64:67], v78 offset1:4
	v_exp_f32_e32 v74, v60
	v_sub_f32_e32 v60, v62, v97
	v_sub_f32_e32 v68, v70, v97
	v_exp_f32_e32 v82, v60
	v_sub_f32_e32 v60, v63, v97
	v_exp_f32_e32 v114, v68
	v_sub_f32_e32 v68, v71, v97
	v_pk_add_f32 v[156:157], v[116:117], 0 op_sel_hi:[1,0]
	v_exp_f32_e32 v80, v60
	v_cvt_pk_bf16_f32 v60, v116, v112
	v_add_u32_e32 v116, 0x5000, v135
	v_exp_f32_e32 v102, v68
	ds_read2_b64 v[68:71], v116 offset0:32 offset1:36
	v_mov_b32_e32 v161, v76
	v_pk_mul_f32 v[146:147], v[54:55], v[76:77] op_sel_hi:[1,0]
	v_pk_mul_f32 v[144:145], v[52:53], v[76:77] op_sel_hi:[1,0]
	v_cvt_pk_bf16_f32 v52, v117, v113
	v_cvt_pk_bf16_f32 v53, v115, v103
	v_cvt_pk_bf16_f32 v54, v105, v109
	v_cvt_pk_bf16_f32 v55, v107, v111
	v_pk_mul_f32 v[38:39], v[38:39], v[160:161] op_sel_hi:[1,0]
	v_pk_mul_f32 v[36:37], v[36:37], v[160:161] op_sel_hi:[1,0]
	v_cvt_pk_bf16_f32 v61, v114, v102
	v_cvt_pk_bf16_f32 v62, v104, v108
	v_cvt_pk_bf16_f32 v63, v106, v110
	v_add_u32_e32 v117, 0x5800, v135
	s_waitcnt lgkmcnt(1)
	v_mfma_f32_16x16x32_bf16 v[144:147], v[64:67], v[52:55], v[144:147]
	v_mul_f32_e64 v150, v50, v76
	v_mul_f32_e64 v151, v51, v76
	v_pk_mul_f32 v[148:149], v[48:49], v[76:77] op_sel_hi:[1,0]
	v_pk_mul_f32 v[34:35], v[34:35], v[160:161] op_sel_hi:[1,0]
	v_mfma_f32_16x16x32_bf16 v[36:39], v[64:67], v[60:63], v[36:39]
	ds_read2_b64 v[64:67], v117 offset0:64 offset1:68
	v_pk_mul_f32 v[32:33], v[32:33], v[160:161] op_sel_hi:[1,0]
	v_add_u32_e32 v162, 0x6000, v135
	s_waitcnt lgkmcnt(1)
	v_mfma_f32_16x16x32_bf16 v[148:151], v[68:71], v[52:55], v[148:151]
	v_mul_f32_e64 v50, v46, v76
	v_mul_f32_e64 v51, v47, v76
	v_pk_mul_f32 v[48:49], v[44:45], v[76:77] op_sel_hi:[1,0]
	v_pk_mul_f32 v[46:47], v[42:43], v[76:77] op_sel_hi:[1,0]
	v_mfma_f32_16x16x32_bf16 v[32:35], v[68:71], v[60:63], v[32:35]
	ds_read2_b64 v[68:71], v162 offset0:96 offset1:100
	v_pk_mul_f32 v[44:45], v[40:41], v[76:77] op_sel_hi:[1,0]
	v_sub_f32_e32 v56, v56, v97
	s_waitcnt lgkmcnt(1)
	v_mfma_f32_16x16x32_bf16 v[152:155], v[64:67], v[52:55], v[48:51]
	v_mul_f32_e64 v30, v30, v160
	v_mul_f32_e64 v31, v31, v160
	v_pk_mul_f32 v[28:29], v[28:29], v[160:161] op_sel_hi:[1,0]
	v_exp_f32_e32 v84, v56
	v_sub_f32_e32 v48, v58, v97
	v_exp_f32_e32 v76, v48
	ds_read2_b64 v[48:51], v78 offset0:8 offset1:12
	v_sub_f32_e32 v56, v57, v97
	v_mfma_f32_16x16x32_bf16 v[28:31], v[64:67], v[60:63], v[28:31]
	v_exp_f32_e32 v86, v56
	v_cvt_pk_bf16_f32 v40, v73, v75
	v_cvt_pk_bf16_f32 v41, v83, v81
	s_waitcnt lgkmcnt(1)
	v_mfma_f32_16x16x32_bf16 v[64:67], v[68:71], v[52:55], v[44:47]
	v_cvt_pk_bf16_f32 v42, v85, v87
	v_cvt_pk_bf16_f32 v43, v77, v79
	v_cvt_pk_bf16_f32 v56, v72, v74
	v_sub_f32_e32 v44, v59, v97
	v_exp_f32_e32 v78, v44
	ds_read2_b64 v[44:47], v116 offset0:40 offset1:44
	v_cvt_pk_bf16_f32 v57, v82, v80
	v_cvt_pk_bf16_f32 v58, v84, v86
	v_cvt_pk_bf16_f32 v59, v76, v78
	v_pk_mul_f32 v[26:27], v[26:27], v[160:161] op_sel_hi:[1,0]
	v_pk_mul_f32 v[24:25], v[24:25], v[160:161] op_sel_hi:[1,0]
	s_waitcnt lgkmcnt(1)
; __device__ __forceinline__ float sigmoidf_(float x) { return __builtin_amdgcn_rcpf(1.f + __expf(-x)); }
; __device__ __forceinline__ f32x4 mfma16(bf16x8 a, bf16x8 b, f32x4 c) { return __builtin_amdgcn_mfma_f32_16x16x32_bf16(a, b, c, 0, 0, 0); }
; __device__ __forceinline__ void nsa_block_step(const bf16_t* Ks, const bf16_t* VT, const bf16x8 (&qf)[2][2], f32x4 (&O)[2][4], float (&m)[2], float (&l)[2],
;                                                int klo, int khi, int r, int q) {
;     ...
; #pragma unroll
;     for (int s2 = 0; s2 < 2; s2++)
; #pragma unroll
;         for (int dt = 0; dt < 4; dt++) {
;             const u32x2 lo = *(const u32x2*)(VT + (dt * 16 + r) * 72 + (2 * s2) * 16 + 4 * q);
;             const u32x2 hi = *(const u32x2*)(VT + (dt * 16 + r) * 72 + (2 * s2 + 1) * 16 + 4 * q);
;             const bf16x8 va = mk_frag(lo, hi);
; #pragma unroll
;             for (int x = 0; x < 2; x++) O[x][dt] = mfma16(va, pbv[x][s2], O[x][dt]);
;         }
; __device__ void phaseN2_task(const Params& p, int task, char* lds, bf16_t* ydst, int ystride, volatile unsigned* uex, char* ldsb) {
;     ...
;             if (nbr != br) {
; #pragma unroll
;                 for (int x = 0; x < 2; x++) {
;                     float lt = l[x];
;                     lt = xrow_sum(lt);
;                     const float sc = sigmoidf_(br == 0 ? gatev[1][x] : gatev[2][x]) / lt;
; #pragma unroll
;                     for (int dt = 0; dt < 4; dt++) { ofl[(wave * 8 + x * 4 + dt) * 64 + lane] += sc * O[x][dt]; O[x][dt] = (f32x4){0.f, 0.f, 0.f, 0.f}; }
;                     m[x] = -1e30f; l[x] = 0.f;
;                 }
;             }
	v_mfma_f32_16x16x32_bf16 v[52:55], v[48:51], v[40:43], v[144:147]
	s_cmp_lg_u32 s52, s34
	s_cselect_b64 vcc, -1, 0
	v_mfma_f32_16x16x32_bf16 v[36:39], v[48:51], v[56:59], v[36:39]
	v_add_f32_e64 v48, v112, v156
	v_add_f32_e64 v49, v113, v157
	v_mfma_f32_16x16x32_bf16 v[24:27], v[68:71], v[60:63], v[24:27]
	v_add_f32_e64 v68, v114, v48
	v_add_f32_e64 v69, v115, v49
	ds_read2_b64 v[60:63], v117 offset0:72 offset1:76
	v_pk_add_f32 v[68:69], v[102:103], v[68:69]
	s_waitcnt lgkmcnt(1)
	v_mfma_f32_16x16x32_bf16 v[48:51], v[44:47], v[40:43], v[148:151]
	v_add_f32_e64 v68, v104, v68
	v_add_f32_e64 v69, v105, v69
	v_pk_add_f32 v[68:69], v[108:109], v[68:69]
	v_mfma_f32_16x16x32_bf16 v[32:35], v[44:47], v[56:59], v[32:35]
	v_add_f32_e64 v44, v106, v68
	v_add_f32_e64 v45, v107, v69
	ds_read2_b64 v[68:71], v162 offset0:104 offset1:108
	v_pk_add_f32 v[102:103], v[110:111], v[44:45]
	s_waitcnt lgkmcnt(1)
	v_mfma_f32_16x16x32_bf16 v[44:47], v[60:63], v[40:43], v[152:155]
	v_add_f32_e64 v72, v72, v102
	v_add_f32_e64 v73, v73, v103
	v_pk_add_f32 v[72:73], v[74:75], v[72:73]
	v_mfma_f32_16x16x32_bf16 v[28:31], v[60:63], v[56:59], v[28:31]
	v_add_f32_e64 v72, v82, v72
	v_add_f32_e64 v73, v83, v73
	v_pk_add_f32 v[60:61], v[80:81], v[72:73]
	s_waitcnt lgkmcnt(0)
	v_mfma_f32_16x16x32_bf16 v[40:43], v[68:71], v[40:43], v[64:67]
	v_add_f32_e64 v60, v84, v60
	v_add_f32_e64 v61, v85, v61
	v_pk_add_f32 v[60:61], v[86:87], v[60:61]
	v_mfma_f32_16x16x32_bf16 v[24:27], v[68:71], v[56:59], v[24:27]
	v_add_f32_e64 v60, v76, v60
	v_add_f32_e64 v61, v77, v61
	v_pk_add_f32 v[60:61], v[78:79], v[60:61]
	s_nop 0
	v_pk_fma_f32 v[100:101], v[100:101], v[160:161], v[60:61]
	s_mov_b32 s45, 0xf0a18f08
	v_sub_f32_e32 v88, v88, v176
	v_sub_f32_e32 v97, v97, v177
	v_cmp_lt_f32_e64 s[46:47], v88, s45
	v_cmp_lt_f32_e64 s[48:49], v97, s45
	v_sub_f32_e32 v176, 0, v88
	v_sub_f32_e32 v177, 0, v97
	v_cndmask_b32_e64 v176, v176, 0, s[46:47]
	v_cndmask_b32_e64 v177, v177, 0, s[48:49]
	v_cndmask_b32_e64 v178, 4.0, v123, s[46:47]
	v_cndmask_b32_e64 v179, 4.0, v123, s[48:49]
	.p2alignl 6, 3212836864
.Ln2_tail:
	s_and_saveexec_b64 s[6:7], vcc
	s_cbranch_execz .LBB0_617
	s_mov_b64 vcc, s[4:5]
	v_cndmask_b32_sdwa v57, v128, v127, vcc dst_sel:WORD_1 dst_unused:UNUSED_PAD src0_sel:DWORD src1_sel:DWORD
	v_mov_b32_e32 v56, v101
	v_mul_f32_e32 v57, 0xbfb8aa3b, v57
	v_exp_f32_e32 v57, v57
	v_permlane16_swap_b32_e32 v101, v56
	v_add_f32_e32 v56, v101, v56
	v_add_f32_e32 v57, 1.0, v57
	v_rcp_f32_e32 v60, v57
	v_mov_b32_e32 v58, v56
	s_nop 1
	v_permlane32_swap_b32_e32 v56, v58
	v_add_f32_e32 v61, v56, v58
	v_div_scale_f32 v56, s[10:11], v61, v61, v60
	v_rcp_f32_e32 v62, v56
	v_mov_b32_e32 v97, 0xf149f2ca
	v_mov_b32_e32 v88, 0xf149f2ca
	v_mov_b32_e32 v176, 0
	v_mov_b32_e32 v177, 0
	v_mov_b32_e32 v178, v123
	v_mov_b32_e32 v179, v123
	v_fma_f32 v57, -v56, v62, 1.0
	v_fmac_f32_e32 v62, v57, v62
	v_div_scale_f32 v57, vcc, v60, v61, v60
	v_mul_f32_e32 v63, v57, v62
	v_fma_f32 v58, -v56, v63, v57
	v_fmac_f32_e32 v63, v58, v62
	v_fma_f32 v64, -v56, v63, v57
	ds_read_b128 v[56:59], v131 offset:35840
	v_div_fmas_f32 v62, v64, v62, v63
	v_div_fixup_f32 v64, v62, v61, v60
	ds_read_b128 v[60:63], v131 offset:36864
	s_waitcnt lgkmcnt(1)
	v_pk_fma_f32 v[54:55], v[54:55], v[64:65], v[58:59] op_sel_hi:[1,0,1]
	v_pk_fma_f32 v[52:53], v[52:53], v[64:65], v[56:57] op_sel_hi:[1,0,1]
	ds_write_b128 v131, v[52:55] offset:35840
	ds_read_b128 v[52:55], v131 offset:37888
	s_waitcnt lgkmcnt(2)
	v_pk_fma_f32 v[50:51], v[50:51], v[64:65], v[62:63] op_sel_hi:[1,0,1]
	v_pk_fma_f32 v[48:49], v[48:49], v[64:65], v[60:61] op_sel_hi:[1,0,1]
	ds_write_b128 v131, v[48:51] offset:36864
	ds_read_b128 v[48:51], v131 offset:38912
	s_waitcnt lgkmcnt(2)
	v_pk_fma_f32 v[46:47], v[46:47], v[64:65], v[54:55] op_sel_hi:[1,0,1]
	v_pk_fma_f32 v[44:45], v[44:45], v[64:65], v[52:53] op_sel_hi:[1,0,1]
	ds_write_b128 v131, v[44:47] offset:37888
	v_cndmask_b32_e64 v45, v133, v93, s[4:5]
	v_lshlrev_b32_e32 v45, 16, v45
	v_mul_f32_e32 v45, 0xbfb8aa3b, v45
	v_exp_f32_e32 v45, v45
	v_mov_b32_e32 v44, v100
	s_nop 1
	v_permlane16_swap_b32_e32 v100, v44
	v_add_f32_e32 v45, 1.0, v45
	v_add_f32_e32 v44, v100, v44
	v_rcp_f32_e32 v45, v45
	v_mov_b32_e32 v46, v44
	s_nop 1
	v_permlane32_swap_b32_e32 v44, v46
	v_add_f32_e32 v44, v44, v46
	v_div_scale_f32 v46, s[4:5], v44, v44, v45
	v_rcp_f32_e32 v47, v46
	s_waitcnt lgkmcnt(1)
	v_pk_fma_f32 v[42:43], v[42:43], v[64:65], v[50:51] op_sel_hi:[1,0,1]
	v_pk_fma_f32 v[40:41], v[40:41], v[64:65], v[48:49] op_sel_hi:[1,0,1]
	ds_write_b128 v131, v[40:43] offset:38912
	v_fma_f32 v40, -v46, v47, 1.0
	v_fmac_f32_e32 v47, v40, v47
	v_div_scale_f32 v40, vcc, v45, v44, v45
	v_mul_f32_e32 v48, v40, v47
	v_fma_f32 v41, -v46, v48, v40
	v_fmac_f32_e32 v48, v41, v47
	v_fma_f32 v46, -v46, v48, v40
	ds_read_b128 v[40:43], v131 offset:39936
	v_div_fmas_f32 v46, v46, v47, v48
	v_div_fixup_f32 v48, v46, v44, v45
	ds_read_b128 v[44:47], v131 offset:40960
	s_waitcnt lgkmcnt(1)
	v_pk_fma_f32 v[38:39], v[38:39], v[48:49], v[42:43] op_sel_hi:[1,0,1]
	v_pk_fma_f32 v[36:37], v[36:37], v[48:49], v[40:41] op_sel_hi:[1,0,1]
	ds_write_b128 v131, v[36:39] offset:39936
	ds_read_b128 v[36:39], v131 offset:41984
	ds_read_b128 v[40:43], v131 offset:43008
	s_waitcnt lgkmcnt(3)
	v_pk_fma_f32 v[34:35], v[34:35], v[48:49], v[46:47] op_sel_hi:[1,0,1]
	v_pk_fma_f32 v[32:33], v[32:33], v[48:49], v[44:45] op_sel_hi:[1,0,1]
	ds_write_b128 v131, v[32:35] offset:40960
	s_waitcnt lgkmcnt(2)
	v_pk_fma_f32 v[30:31], v[30:31], v[48:49], v[38:39] op_sel_hi:[1,0,1]
	s_waitcnt lgkmcnt(1)
	v_pk_fma_f32 v[26:27], v[26:27], v[48:49], v[42:43] op_sel_hi:[1,0,1]
	v_pk_fma_f32 v[24:25], v[24:25], v[48:49], v[40:41] op_sel_hi:[1,0,1]
	v_pk_fma_f32 v[28:29], v[28:29], v[48:49], v[36:37] op_sel_hi:[1,0,1]
	ds_write_b128 v131, v[24:27] offset:43008
	v_mov_b32_e32 v24, 0
	ds_write_b128 v131, v[28:31] offset:41984
	v_mov_b32_e32 v25, v24
	v_mov_b32_e32 v26, v24
	v_mov_b32_e32 v27, v24
	v_mov_b32_e32 v28, v24
	v_mov_b32_e32 v29, v24
	v_mov_b32_e32 v30, v24
	v_mov_b32_e32 v31, v24
	v_mov_b32_e32 v32, v24
	v_mov_b32_e32 v33, v24
	v_mov_b32_e32 v34, v24
	v_mov_b32_e32 v35, v24
	v_mov_b32_e32 v36, v24
	v_mov_b32_e32 v37, v24
	v_mov_b32_e32 v38, v24
	v_mov_b32_e32 v39, v24
	v_mov_b32_e32 v40, v24
	v_mov_b32_e32 v41, v24
	v_mov_b32_e32 v42, v24
	v_mov_b32_e32 v43, v24
	v_mov_b32_e32 v44, v24
	v_mov_b32_e32 v45, v24
	v_mov_b32_e32 v46, v24
	v_mov_b32_e32 v47, v24
	v_mov_b32_e32 v48, v24
	v_mov_b32_e32 v49, v24
	v_mov_b32_e32 v50, v24
	v_mov_b32_e32 v51, v24
	v_mov_b32_e32 v52, v24
	v_mov_b32_e32 v53, v24
	v_mov_b32_e32 v54, v24
	v_mov_b32_e32 v55, v24
	v_mov_b32_e32 v100, v24
	v_mov_b32_e32 v101, v24
	s_branch .LBB0_617
	.p2alignl 6, 3212836864
